# FF1 + gates GEMM: first two K-loop waits after an epilogue use vmcnt(24) (exact; stores no longer drained in order), on top of v22
# speedup vs baseline: 1.0046x; 1.0046x over previous
; #define PG8_STAGE(bufoff, gbase, voff) do { _Pragma("unroll") for (int _i = 0; _i < 2; ++_i) \
;         __builtin_amdgcn_global_load_lds((const unsigned*)((const char*)(gbase) + (voff)[_i]), (PG8_LAS unsigned*)(lds + (bufoff) + ldsw + _i * 8192), 16, 0, 0); } while (0)
; #define PG8_WAIT_V(n) asm volatile("s_waitcnt vmcnt(" #n ")" ::: "memory")
; #define PG8_BAR __builtin_amdgcn_s_barrier()
; template <class Epi, class Sched, bool ALIGN_EPI = false, bool SP2 = false>
; __device__ __forceinline__ void gemm_phase(PG8_LAS unsigned char* lds, const Gemm g, const Sched& S, const Epi& E, const int tid_in) {
;     ...
;     if constexpr (SP2) {
;         PG8_STAGE(PG8_SB(0, 0), cB, voffB); PG8_STAGE(PG8_SB(0, 1), cB + hstep, voffB); PG8_STAGE(PG8_SA(0, 0), cA, voffA); PG8_STAGE(PG8_SA(0, 1), cA + hstepA, voffA);
;         if (wr == 1) PG8_BAR;
;         PG8_WAIT_V(2); PG8_BAR;
;         PG8_STAGE(PG8_SB(1, 0), cB + kstep, voffB); PG8_STAGE(PG8_SA(1, 0), cA + kstepA, voffA); PG8_STAGE(PG8_SB(1, 1), cB + hstep + kstep, voffB);
;         PG8_WAIT_V(6); PG8_BAR;
.LBB0_904:
	v_and_b32_e32 v11, 48, v4
	v_lshlrev_b32_e32 v16, 6, v4
	s_movk_i32 s7, 0x3c0
	v_lshlrev_b32_e32 v4, 2, v4
	s_lshl_b32 s6, s12, 13
	v_and_or_b32 v11, v16, s7, v11
	v_and_b32_e32 v4, 32, v4
	v_readlane_b32 s56, v254, 45
	v_bitop3_b32 v16, v11, s6, v4 bitop3:0xde
	s_lshl_b32 s6, s14, 5
	v_mov_b32_e32 v145, v185
	v_readlane_b32 s57, v254, 46
	s_and_b32 s67, s6, 0x60
	s_add_i32 m0, s62, 0x18000
	v_lshl_add_u64 v[0:1], v[0:1], 0, s[84:85]
	v_lshl_add_u64 v[12:13], s[56:57], 0, v[144:145]
	v_mov_b32_e32 v147, v185
	s_lshl_b32 s66, s12, 6
	s_lshl_b32 s6, s67, 7
	s_waitcnt vmcnt(2)
	s_barrier
	global_load_lds_dwordx4 v[0:1], off
	v_lshl_add_u64 v[0:1], v[2:3], 0, s[84:85]
	s_add_i32 m0, s62, 0x1a000
	s_add_i32 s68, s62, 0x8000
	s_add_i32 s69, s62, 0xa000
	v_lshl_add_u64 v[14:15], s[56:57], 0, v[146:147]
	global_load_lds_dwordx4 v[0:1], off
	v_lshl_add_u64 v[0:1], v[12:13], 0, s[84:85]
	s_mov_b32 m0, s68
	s_add_u32 s14, s58, 0x40080
	global_load_lds_dwordx4 v[0:1], off
	v_lshl_add_u64 v[0:1], v[14:15], 0, s[84:85]
	s_mov_b32 m0, s69
	s_addc_u32 s15, s59, 0
	global_load_lds_dwordx4 v[0:1], off
	s_add_i32 m0, s62, 0x1c000
	v_lshl_add_u64 v[0:1], s[14:15], 0, v[184:185]
	global_load_lds_dwordx4 v[0:1], off
	v_lshl_add_u64 v[0:1], s[14:15], 0, v[148:149]
	s_add_i32 m0, s62, 0x1e000
	v_bitop3_b32 v154, s6, v11, v4 bitop3:0xf6
	global_load_lds_dwordx4 v[0:1], off
	v_lshlrev_b32_e32 v0, 14, v5
	v_and_b32_e32 v0, 0xffff8000, v0
	v_lshl_add_u32 v0, v6, 11, v0
	v_and_b32_e32 v1, 1, v5
	v_lshl_or_b32 v0, v1, 6, v0
	v_lshl_add_u32 v150, v7, 1, v0
	v_lshlrev_b32_e32 v0, 14, v8
	v_and_b32_e32 v0, 0xffff8000, v0
	s_waitcnt vmcnt(6)
	v_lshl_add_u32 v0, v9, 11, v0
	v_and_b32_e32 v1, 1, v8
	s_cmpk_lt_u32 s3, 0x100
	v_lshl_or_b32 v0, v1, 6, v0
	v_readlane_b32 s6, v254, 42
	s_cselect_b64 s[40:41], -1, 0
	v_mov_b32_e32 v151, v185
	v_lshl_add_u32 v152, v10, 1, v0
	v_mov_b32_e32 v153, v185
	s_mov_b32 s78, 0
	v_add_u32_e32 v155, 0, v16
	v_readlane_b32 s79, v254, 40
	s_mov_b32 s71, s6
	s_barrier
	v_readlane_b32 s7, v254, 43
	s_mov_b32 s100, 0
	s_branch .LBB0_907

; #define PG8_BAR __builtin_amdgcn_s_barrier()
; template <class Epi, class Sched, bool ALIGN_EPI = false, bool SP2 = false>
; __device__ __forceinline__ void gemm_phase(PG8_LAS unsigned char* lds, const Gemm g, const Sched& S, const Epi& E, const int tid_in) {
;     ...
;         cur = nxt; cA = nA; cB = nB; ++ui;
;         if constexpr (ALIGN_EPI) { if (wr == 1) PG8_BAR; }
.LBB0_906:
	s_mov_b32 s100, 1
	s_mov_b64 s[58:59], s[50:51]
	v_readlane_b32 s50, v251, 3
	s_andn2_b64 vcc, exec, s[34:35]
	s_mov_b32 s79, s42
	s_mov_b32 s71, s44
	s_mov_b64 s[56:57], s[46:47]
	s_mov_b32 s78, s70
	v_readlane_b32 s51, v251, 4
	s_cbranch_vccz .LBB0_926

; #define PG8_STAGE(bufoff, gbase, voff) do { _Pragma("unroll") for (int _i = 0; _i < 2; ++_i) \
;         __builtin_amdgcn_global_load_lds((const unsigned*)((const char*)(gbase) + (voff)[_i]), (PG8_LAS unsigned*)(lds + (bufoff) + ldsw + _i * 8192), 16, 0, 0); } while (0)
; #define PG8_LDA(dst, b, h) do { _Pragma("unroll") for (int m = 0; m < 4; ++m) _Pragma("unroll") for (int k = 0; k < 2; ++k) dst[m][k] = *(const PG8_LAS bf16x8*)(lds + PG8_SA(b, h) + aoff + m * 2048 + k * 1024); } while (0)
; #define PG8_LDB(dst, b, h) do { _Pragma("unroll") for (int n = 0; n < 2; ++n) _Pragma("unroll") for (int k = 0; k < 2; ++k) dst[n][k] = *(const PG8_LAS bf16x8*)(lds + PG8_SB(b, h) + boff + n * 2048 + k * 1024); } while (0)
; #define PG8_MMA(ai, bj, At, Bt) do { __builtin_amdgcn_s_setprio(1); _Pragma("unroll") for (int m = 0; m < 4; ++m) _Pragma("unroll") for (int n = 0; n < 2; ++n) _Pragma("unroll") for (int k = 0; k < 2; ++k) \
;         acc[ai][bj][m][n] = __builtin_amdgcn_mfma_f32_16x16x32_bf16(Bt[n][k], At[m][k], acc[ai][bj][m][n], 0, 0, 0); __builtin_amdgcn_s_setprio(0); } while (0)
; #define PG8_WAIT_V(n) asm volatile("s_waitcnt vmcnt(" #n ")" ::: "memory")
; #define PG8_WAIT_L(n) asm volatile("s_waitcnt lgkmcnt(" #n ")" ::: "memory")
; #define PG8_BAR __builtin_amdgcn_s_barrier()
; #define PG8_SCHED __builtin_amdgcn_sched_barrier(0)
; template <class Epi, class Sched, bool ALIGN_EPI = false, bool SP2 = false>
; __device__ __forceinline__ void gemm_phase(PG8_LAS unsigned char* lds, const Gemm g, const Sched& S, const Epi& E, const int tid_in) {
;     ...
;             PG8_LDB(B0, 0, 0); PG8_LDB(B1, 0, 1); PG8_SCHED; PG8_LDA(At, 0, 0); PG8_STAGE(PG8_SA(1, 1), a1 + hstepA, voffA);
;             PG8_WAIT_V(8); PG8_WAIT_L(0); PG8_BAR; PG8_MMA(0, 0, At, B0); PG8_MMA(0, 1, At, B1); PG8_BAR; PG8_SCHED;
;             PG8_LDA(At, 0, 1); PG8_STAGE(PG8_SB(0, 0), b2, voffB); PG8_STAGE(PG8_SB(0, 1), b2 + hstep, voffB); PG8_STAGE(PG8_SA(0, 0), a2, voffA);
.LBB0_915:
	s_add_u32 s6, s56, 0xfffc0080
	s_addc_u32 s7, s57, -1
	s_and_b64 s[58:59], s[58:59], exec
	s_cselect_b32 s61, s3, s7
	s_cselect_b32 s60, s12, s6
	s_cselect_b32 s59, s43, s14
	s_cselect_b32 s58, s45, s77
	s_add_i32 s6, 0, 0x10000
	s_add_i32 s7, 0, 0x14000
	v_add_u32_e32 v124, s6, v154
	v_add_u32_e32 v168, s7, v154
	ds_read_b128 v[104:107], v124
	ds_read_b128 v[112:115], v124 offset:1024
	ds_read_b128 v[120:123], v124 offset:2048
	ds_read_b128 v[124:127], v124 offset:3072
	ds_read_b128 v[156:159], v168
	ds_read_b128 v[160:163], v168 offset:1024
	ds_read_b128 v[164:167], v168 offset:2048
	ds_read_b128 v[168:171], v168 offset:3072
	v_lshl_add_u64 v[190:191], s[56:57], 0, v[150:151]
	s_add_i32 m0, s62, 0xc000
	ds_read_b128 v[172:175], v155
	ds_read_b128 v[176:179], v155 offset:1024
	ds_read_b128 v[180:183], v155 offset:2048
	ds_read_b128 v[186:189], v155 offset:3072
	ds_read_b128 v[194:197], v155 offset:4096
	ds_read_b128 v[198:201], v155 offset:5120
	ds_read_b128 v[202:205], v155 offset:6144
	ds_read_b128 v[206:209], v155 offset:7168
	global_load_lds_dwordx4 v[190:191], off
	v_lshl_add_u64 v[190:191], s[56:57], 0, v[152:153]
	s_add_i32 m0, s62, 0xe000
	s_nop 0
	global_load_lds_dwordx4 v[190:191], off
	s_cmp_eq_u32 s100, 0
	s_cbranch_scc1 .Llbb0_915_strict1
	s_waitcnt vmcnt(24)
	s_branch .Llbb0_915_done1
.Llbb0_915_strict1:
	s_waitcnt vmcnt(8)
.Llbb0_915_done1:
	s_waitcnt lgkmcnt(0)
	s_barrier
	s_setprio 1
	s_waitcnt lgkmcnt(0)
	v_mfma_f32_16x16x32_bf16 v[140:143], v[104:107], v[172:175], v[140:143]
	v_mfma_f32_16x16x32_bf16 v[136:139], v[120:123], v[172:175], v[136:139]
	v_mfma_f32_16x16x32_bf16 v[116:119], v[104:107], v[180:183], v[116:119]
	v_mfma_f32_16x16x32_bf16 v[108:111], v[120:123], v[180:183], v[108:111]
	v_mfma_f32_16x16x32_bf16 v[92:95], v[104:107], v[194:197], v[92:95]
	v_mfma_f32_16x16x32_bf16 v[88:91], v[120:123], v[194:197], v[88:91]
	v_mfma_f32_16x16x32_bf16 v[76:79], v[104:107], v[202:205], v[76:79]
	v_mfma_f32_16x16x32_bf16 v[72:75], v[120:123], v[202:205], v[72:75]
	v_mfma_f32_16x16x32_bf16 v[140:143], v[112:115], v[176:179], v[140:143]
	v_mfma_f32_16x16x32_bf16 v[136:139], v[124:127], v[176:179], v[136:139]
	v_mfma_f32_16x16x32_bf16 v[116:119], v[112:115], v[186:189], v[116:119]
	v_mfma_f32_16x16x32_bf16 v[108:111], v[124:127], v[186:189], v[108:111]
	v_mfma_f32_16x16x32_bf16 v[92:95], v[112:115], v[198:201], v[92:95]
	v_mfma_f32_16x16x32_bf16 v[88:91], v[124:127], v[198:201], v[88:91]
	v_mfma_f32_16x16x32_bf16 v[76:79], v[112:115], v[206:209], v[76:79]
	v_mfma_f32_16x16x32_bf16 v[72:75], v[124:127], v[206:209], v[72:75]
	s_setprio 0
	s_setprio 1
	v_mfma_f32_16x16x32_bf16 v[132:135], v[156:159], v[172:175], v[132:135]
	v_mfma_f32_16x16x32_bf16 v[128:131], v[164:167], v[172:175], v[128:131]
	v_mfma_f32_16x16x32_bf16 v[100:103], v[156:159], v[180:183], v[100:103]
	v_mfma_f32_16x16x32_bf16 v[96:99], v[164:167], v[180:183], v[96:99]
	v_mfma_f32_16x16x32_bf16 v[84:87], v[156:159], v[194:197], v[84:87]
	v_mfma_f32_16x16x32_bf16 v[80:83], v[164:167], v[194:197], v[80:83]
	v_mfma_f32_16x16x32_bf16 v[68:71], v[156:159], v[202:205], v[68:71]
	v_mfma_f32_16x16x32_bf16 v[64:67], v[164:167], v[202:205], v[64:67]
	v_mfma_f32_16x16x32_bf16 v[132:135], v[160:163], v[176:179], v[132:135]
	v_mfma_f32_16x16x32_bf16 v[128:131], v[168:171], v[176:179], v[128:131]
	v_mfma_f32_16x16x32_bf16 v[100:103], v[160:163], v[186:189], v[100:103]
	v_mfma_f32_16x16x32_bf16 v[96:99], v[168:171], v[186:189], v[96:99]
	v_mfma_f32_16x16x32_bf16 v[84:87], v[160:163], v[198:201], v[84:87]
	v_mfma_f32_16x16x32_bf16 v[80:83], v[168:171], v[198:201], v[80:83]
	v_mfma_f32_16x16x32_bf16 v[68:71], v[160:163], v[206:209], v[68:71]
	v_mfma_f32_16x16x32_bf16 v[64:67], v[168:171], v[206:209], v[64:67]
	s_setprio 0
	s_barrier
	s_add_i32 s6, s6, s54
	v_lshl_add_u64 v[190:191], s[58:59], 0, v[184:185]
	s_mov_b32 m0, s6
	ds_read_b128 v[172:175], v155 offset:16384
	ds_read_b128 v[176:179], v155 offset:17408
	ds_read_b128 v[180:183], v155 offset:18432
	ds_read_b128 v[186:189], v155 offset:19456
	ds_read_b128 v[194:197], v155 offset:20480
	ds_read_b128 v[198:201], v155 offset:21504
	ds_read_b128 v[202:205], v155 offset:22528
	ds_read_b128 v[206:209], v155 offset:23552
	global_load_lds_dwordx4 v[190:191], off
	s_add_i32 m0, s6, 0x2000
	s_add_u32 vcc_lo, s58, 0x40000
	v_lshl_add_u64 v[192:193], s[58:59], 0, v[148:149]
	s_addc_u32 vcc_hi, s59, 0
	s_add_i32 s6, s7, s54
	global_load_lds_dwordx4 v[192:193], off
	v_lshl_add_u64 v[210:211], vcc, 0, v[184:185]
	s_mov_b32 m0, s6
	v_lshl_add_u64 v[212:213], s[60:61], 0, v[146:147]
	global_load_lds_dwordx4 v[210:211], off
	v_lshl_add_u64 v[210:211], vcc, 0, v[148:149]
	s_add_i32 m0, s6, 0x2000
	s_nop 0
	global_load_lds_dwordx4 v[210:211], off
	v_lshl_add_u64 v[210:211], s[60:61], 0, v[144:145]
	s_mov_b32 m0, s62
	s_nop 0
	global_load_lds_dwordx4 v[210:211], off
	s_mov_b32 m0, s63
	s_nop 0
	global_load_lds_dwordx4 v[212:213], off
	s_cmp_eq_u32 s100, 0
	s_cbranch_scc1 .Llbb0_915_strict2
	s_waitcnt vmcnt(24)
	s_branch .Llbb0_915_done2

; #define PG8_STAGE(bufoff, gbase, voff) do { _Pragma("unroll") for (int _i = 0; _i < 2; ++_i) \
;         __builtin_amdgcn_global_load_lds((const unsigned*)((const char*)(gbase) + (voff)[_i]), (PG8_LAS unsigned*)(lds + (bufoff) + ldsw + _i * 8192), 16, 0, 0); } while (0)
; #define PG8_LDA(dst, b, h) do { _Pragma("unroll") for (int m = 0; m < 4; ++m) _Pragma("unroll") for (int k = 0; k < 2; ++k) dst[m][k] = *(const PG8_LAS bf16x8*)(lds + PG8_SA(b, h) + aoff + m * 2048 + k * 1024); } while (0)
; #define PG8_LDB(dst, b, h) do { _Pragma("unroll") for (int n = 0; n < 2; ++n) _Pragma("unroll") for (int k = 0; k < 2; ++k) dst[n][k] = *(const PG8_LAS bf16x8*)(lds + PG8_SB(b, h) + boff + n * 2048 + k * 1024); } while (0)
; #define PG8_MMA(ai, bj, At, Bt) do { __builtin_amdgcn_s_setprio(1); _Pragma("unroll") for (int m = 0; m < 4; ++m) _Pragma("unroll") for (int n = 0; n < 2; ++n) _Pragma("unroll") for (int k = 0; k < 2; ++k) \
;         acc[ai][bj][m][n] = __builtin_amdgcn_mfma_f32_16x16x32_bf16(Bt[n][k], At[m][k], acc[ai][bj][m][n], 0, 0, 0); __builtin_amdgcn_s_setprio(0); } while (0)
; #define PG8_WAIT_V(n) asm volatile("s_waitcnt vmcnt(" #n ")" ::: "memory")
; #define PG8_WAIT_L(n) asm volatile("s_waitcnt lgkmcnt(" #n ")" ::: "memory")
; #define PG8_BAR __builtin_amdgcn_s_barrier()
; #define PG8_SCHED __builtin_amdgcn_sched_barrier(0)
; template <class Epi, class Sched, bool ALIGN_EPI = false, bool SP2 = false>
; __device__ __forceinline__ void gemm_phase(PG8_LAS unsigned char* lds, const Gemm g, const Sched& S, const Epi& E, const int tid_in) {
;     ...
;             PG8_LDA(At, 0, 1); PG8_STAGE(PG8_SB(0, 0), b2, voffB); PG8_STAGE(PG8_SB(0, 1), b2 + hstep, voffB); PG8_STAGE(PG8_SA(0, 0), a2, voffA);
;             PG8_WAIT_V(8); PG8_WAIT_L(0); PG8_BAR; PG8_MMA(1, 0, At, B0); PG8_MMA(1, 1, At, B1); PG8_BAR; PG8_SCHED;
;             PG8_LDB(B0, 1, 0); PG8_LDB(B1, 1, 1); PG8_SCHED; PG8_LDA(At, 1, 0); PG8_STAGE(PG8_SA(0, 1), a2 + hstepA, voffA);
;             PG8_WAIT_V(8); PG8_WAIT_L(0); PG8_BAR; PG8_MMA(0, 0, At, B0); PG8_MMA(0, 1, At, B1); PG8_BAR; PG8_SCHED;
.Llbb0_915_done2:
	s_mov_b32 s100, 0
	s_waitcnt lgkmcnt(0)
	s_barrier
	s_setprio 1
	s_waitcnt lgkmcnt(0)
	v_mfma_f32_16x16x32_bf16 v[60:63], v[104:107], v[172:175], v[60:63]
	v_mfma_f32_16x16x32_bf16 v[56:59], v[120:123], v[172:175], v[56:59]
	v_mfma_f32_16x16x32_bf16 v[44:47], v[104:107], v[180:183], v[44:47]
	v_mfma_f32_16x16x32_bf16 v[40:43], v[120:123], v[180:183], v[40:43]
	v_mfma_f32_16x16x32_bf16 v[28:31], v[104:107], v[194:197], v[28:31]
	v_mfma_f32_16x16x32_bf16 v[24:27], v[120:123], v[194:197], v[24:27]
	v_mfma_f32_16x16x32_bf16 v[12:15], v[104:107], v[202:205], v[12:15]
	v_mfma_f32_16x16x32_bf16 v[8:11], v[120:123], v[202:205], v[8:11]
	v_mfma_f32_16x16x32_bf16 v[60:63], v[112:115], v[176:179], v[60:63]
	v_mfma_f32_16x16x32_bf16 v[56:59], v[124:127], v[176:179], v[56:59]
	v_mfma_f32_16x16x32_bf16 v[44:47], v[112:115], v[186:189], v[44:47]
	v_mfma_f32_16x16x32_bf16 v[40:43], v[124:127], v[186:189], v[40:43]
	v_mfma_f32_16x16x32_bf16 v[28:31], v[112:115], v[198:201], v[28:31]
	v_mfma_f32_16x16x32_bf16 v[24:27], v[124:127], v[198:201], v[24:27]
	v_mfma_f32_16x16x32_bf16 v[12:15], v[112:115], v[206:209], v[12:15]
	v_mfma_f32_16x16x32_bf16 v[8:11], v[124:127], v[206:209], v[8:11]
	s_setprio 0
	s_setprio 1
	v_mfma_f32_16x16x32_bf16 v[52:55], v[156:159], v[172:175], v[52:55]
	v_mfma_f32_16x16x32_bf16 v[48:51], v[164:167], v[172:175], v[48:51]
	v_mfma_f32_16x16x32_bf16 v[36:39], v[156:159], v[180:183], v[36:39]
	v_mfma_f32_16x16x32_bf16 v[32:35], v[164:167], v[180:183], v[32:35]
	v_mfma_f32_16x16x32_bf16 v[20:23], v[156:159], v[194:197], v[20:23]
	v_mfma_f32_16x16x32_bf16 v[16:19], v[164:167], v[194:197], v[16:19]
	v_mfma_f32_16x16x32_bf16 v[4:7], v[156:159], v[202:205], v[4:7]
	v_mfma_f32_16x16x32_bf16 v[0:3], v[164:167], v[202:205], v[0:3]
	v_mfma_f32_16x16x32_bf16 v[52:55], v[160:163], v[176:179], v[52:55]
	v_mfma_f32_16x16x32_bf16 v[48:51], v[168:171], v[176:179], v[48:51]
	v_mfma_f32_16x16x32_bf16 v[36:39], v[160:163], v[186:189], v[36:39]
	v_mfma_f32_16x16x32_bf16 v[32:35], v[168:171], v[186:189], v[32:35]
	v_mfma_f32_16x16x32_bf16 v[20:23], v[160:163], v[198:201], v[20:23]
	v_mfma_f32_16x16x32_bf16 v[16:19], v[168:171], v[198:201], v[16:19]
	v_mfma_f32_16x16x32_bf16 v[4:7], v[160:163], v[206:209], v[4:7]
	v_mfma_f32_16x16x32_bf16 v[0:3], v[168:171], v[206:209], v[0:3]
	s_setprio 0
	s_barrier
	s_add_i32 s6, 0, 0x18000
	s_add_i32 s7, 0, 0x1c000
	v_add_u32_e32 v124, s6, v154
	v_add_u32_e32 v168, s7, v154
	ds_read_b128 v[104:107], v124
	ds_read_b128 v[112:115], v124 offset:1024
	ds_read_b128 v[120:123], v124 offset:2048
	ds_read_b128 v[124:127], v124 offset:3072
	ds_read_b128 v[156:159], v168
	ds_read_b128 v[160:163], v168 offset:1024
	ds_read_b128 v[164:167], v168 offset:2048
	ds_read_b128 v[168:171], v168 offset:3072
	s_add_u32 s60, s60, 0x40000
	s_addc_u32 s61, s61, 0
	s_mov_b32 m0, s64
	v_lshl_add_u64 v[214:215], s[60:61], 0, v[144:145]
	ds_read_b128 v[172:175], v155 offset:32768
	ds_read_b128 v[176:179], v155 offset:33792
	ds_read_b128 v[180:183], v155 offset:34816
	ds_read_b128 v[186:189], v155 offset:35840
	ds_read_b128 v[194:197], v155 offset:36864
	ds_read_b128 v[198:201], v155 offset:37888
	ds_read_b128 v[202:205], v155 offset:38912
	ds_read_b128 v[206:209], v155 offset:39936
	global_load_lds_dwordx4 v[214:215], off
	v_lshl_add_u64 v[214:215], s[60:61], 0, v[146:147]
	s_mov_b32 m0, s65
	s_nop 0
	global_load_lds_dwordx4 v[214:215], off
	s_waitcnt vmcnt(8)
	s_waitcnt lgkmcnt(0)
	s_barrier
	s_setprio 1
	s_waitcnt lgkmcnt(0)
	v_mfma_f32_16x16x32_bf16 v[140:143], v[104:107], v[172:175], v[140:143]
	v_mfma_f32_16x16x32_bf16 v[136:139], v[120:123], v[172:175], v[136:139]
	v_mfma_f32_16x16x32_bf16 v[116:119], v[104:107], v[180:183], v[116:119]
	v_mfma_f32_16x16x32_bf16 v[108:111], v[120:123], v[180:183], v[108:111]
	v_mfma_f32_16x16x32_bf16 v[92:95], v[104:107], v[194:197], v[92:95]
	v_mfma_f32_16x16x32_bf16 v[88:91], v[120:123], v[194:197], v[88:91]
	v_mfma_f32_16x16x32_bf16 v[76:79], v[104:107], v[202:205], v[76:79]
	v_mfma_f32_16x16x32_bf16 v[72:75], v[120:123], v[202:205], v[72:75]
	v_mfma_f32_16x16x32_bf16 v[140:143], v[112:115], v[176:179], v[140:143]
	v_mfma_f32_16x16x32_bf16 v[136:139], v[124:127], v[176:179], v[136:139]
	v_mfma_f32_16x16x32_bf16 v[116:119], v[112:115], v[186:189], v[116:119]
	v_mfma_f32_16x16x32_bf16 v[108:111], v[124:127], v[186:189], v[108:111]
	v_mfma_f32_16x16x32_bf16 v[92:95], v[112:115], v[198:201], v[92:95]
	v_mfma_f32_16x16x32_bf16 v[88:91], v[124:127], v[198:201], v[88:91]
	v_mfma_f32_16x16x32_bf16 v[76:79], v[112:115], v[206:209], v[76:79]
	v_mfma_f32_16x16x32_bf16 v[72:75], v[124:127], v[206:209], v[72:75]
	s_setprio 0
	s_setprio 1
	v_mfma_f32_16x16x32_bf16 v[132:135], v[156:159], v[172:175], v[132:135]
	v_mfma_f32_16x16x32_bf16 v[128:131], v[164:167], v[172:175], v[128:131]
	v_mfma_f32_16x16x32_bf16 v[100:103], v[156:159], v[180:183], v[100:103]
	v_mfma_f32_16x16x32_bf16 v[96:99], v[164:167], v[180:183], v[96:99]
	v_mfma_f32_16x16x32_bf16 v[84:87], v[156:159], v[194:197], v[84:87]
	v_mfma_f32_16x16x32_bf16 v[80:83], v[164:167], v[194:197], v[80:83]
	v_mfma_f32_16x16x32_bf16 v[68:71], v[156:159], v[202:205], v[68:71]
	v_mfma_f32_16x16x32_bf16 v[64:67], v[164:167], v[202:205], v[64:67]
	v_mfma_f32_16x16x32_bf16 v[132:135], v[160:163], v[176:179], v[132:135]
	v_mfma_f32_16x16x32_bf16 v[128:131], v[168:171], v[176:179], v[128:131]
	v_mfma_f32_16x16x32_bf16 v[100:103], v[160:163], v[186:189], v[100:103]
	v_mfma_f32_16x16x32_bf16 v[96:99], v[168:171], v[186:189], v[96:99]
	v_mfma_f32_16x16x32_bf16 v[84:87], v[160:163], v[198:201], v[84:87]
	v_mfma_f32_16x16x32_bf16 v[80:83], v[168:171], v[198:201], v[80:83]
	v_mfma_f32_16x16x32_bf16 v[68:71], v[160:163], v[206:209], v[68:71]
	v_mfma_f32_16x16x32_bf16 v[64:67], v[168:171], v[206:209], v[64:67]
	s_setprio 0
	s_barrier
; #define PG8_STAGE(bufoff, gbase, voff) do { _Pragma("unroll") for (int _i = 0; _i < 2; ++_i) \
;         __builtin_amdgcn_global_load_lds((const unsigned*)((const char*)(gbase) + (voff)[_i]), (PG8_LAS unsigned*)(lds + (bufoff) + ldsw + _i * 8192), 16, 0, 0); } while (0)
; #define PG8_LDA(dst, b, h) do { _Pragma("unroll") for (int m = 0; m < 4; ++m) _Pragma("unroll") for (int k = 0; k < 2; ++k) dst[m][k] = *(const PG8_LAS bf16x8*)(lds + PG8_SA(b, h) + aoff + m * 2048 + k * 1024); } while (0)
; #define PG8_MMA(ai, bj, At, Bt) do { __builtin_amdgcn_s_setprio(1); _Pragma("unroll") for (int m = 0; m < 4; ++m) _Pragma("unroll") for (int n = 0; n < 2; ++n) _Pragma("unroll") for (int k = 0; k < 2; ++k) \
;         acc[ai][bj][m][n] = __builtin_amdgcn_mfma_f32_16x16x32_bf16(Bt[n][k], At[m][k], acc[ai][bj][m][n], 0, 0, 0); __builtin_amdgcn_s_setprio(0); } while (0)
; #define PG8_WAIT_V(n) asm volatile("s_waitcnt vmcnt(" #n ")" ::: "memory")
; #define PG8_WAIT_L(n) asm volatile("s_waitcnt lgkmcnt(" #n ")" ::: "memory")
; #define PG8_BAR __builtin_amdgcn_s_barrier()
; #define PG8_SCHED __builtin_amdgcn_sched_barrier(0)
; template <class Epi, class Sched, bool ALIGN_EPI = false, bool SP2 = false>
; __device__ __forceinline__ void gemm_phase(PG8_LAS unsigned char* lds, const Gemm g, const Sched& S, const Epi& E, const int tid_in) {
;     ...
;             PG8_LDA(At, 1, 1); PG8_STAGE(PG8_SB(1, 0), b3, voffB); PG8_STAGE(PG8_SB(1, 1), b3 + hstep, voffB); PG8_STAGE(PG8_SA(1, 0), a3, voffA);
;             PG8_WAIT_V(8); PG8_WAIT_L(0); PG8_BAR; PG8_MMA(1, 0, At, B0); PG8_MMA(1, 1, At, B1); PG8_BAR; PG8_SCHED;
	s_add_i32 s6, s6, s54
	v_lshl_add_u64 v[190:191], v[190:191], 0, s[84:85]
	s_mov_b32 m0, s6
	ds_read_b128 v[172:175], v155 offset:49152
	ds_read_b128 v[176:179], v155 offset:50176
	ds_read_b128 v[180:183], v155 offset:51200
	ds_read_b128 v[186:189], v155 offset:52224
	ds_read_b128 v[194:197], v155 offset:53248
	ds_read_b128 v[198:201], v155 offset:54272
	ds_read_b128 v[202:205], v155 offset:55296
	ds_read_b128 v[206:209], v155 offset:56320
	global_load_lds_dwordx4 v[190:191], off
	s_add_i32 m0, s6, 0x2000
	s_add_u32 s58, s58, 0x40080
	v_lshl_add_u64 v[190:191], v[192:193], 0, s[84:85]
	s_addc_u32 s59, s59, 0
	s_add_i32 s6, s7, s54
	global_load_lds_dwordx4 v[190:191], off
	v_lshl_add_u64 v[190:191], s[58:59], 0, v[184:185]
	s_mov_b32 m0, s6
	s_nop 0
	global_load_lds_dwordx4 v[190:191], off
	v_lshl_add_u64 v[190:191], s[58:59], 0, v[148:149]
	s_add_i32 m0, s6, 0x2000
	s_nop 0
	global_load_lds_dwordx4 v[190:191], off
	v_lshl_add_u64 v[190:191], v[210:211], 0, s[84:85]
	s_mov_b32 m0, s68
	s_nop 0
	global_load_lds_dwordx4 v[190:191], off
	v_lshl_add_u64 v[190:191], v[212:213], 0, s[84:85]
	s_mov_b32 m0, s69
	s_nop 0
	global_load_lds_dwordx4 v[190:191], off
	s_waitcnt vmcnt(8)
	s_waitcnt lgkmcnt(0)
	s_barrier
	s_setprio 1
	s_waitcnt lgkmcnt(0)
	v_mfma_f32_16x16x32_bf16 v[60:63], v[104:107], v[172:175], v[60:63]
	v_mfma_f32_16x16x32_bf16 v[56:59], v[120:123], v[172:175], v[56:59]
	v_mfma_f32_16x16x32_bf16 v[44:47], v[104:107], v[180:183], v[44:47]
	v_mfma_f32_16x16x32_bf16 v[40:43], v[120:123], v[180:183], v[40:43]
	v_mfma_f32_16x16x32_bf16 v[28:31], v[104:107], v[194:197], v[28:31]
	v_mfma_f32_16x16x32_bf16 v[24:27], v[120:123], v[194:197], v[24:27]
	v_mfma_f32_16x16x32_bf16 v[12:15], v[104:107], v[202:205], v[12:15]
	v_mfma_f32_16x16x32_bf16 v[8:11], v[120:123], v[202:205], v[8:11]
	v_mfma_f32_16x16x32_bf16 v[60:63], v[112:115], v[176:179], v[60:63]
	v_mfma_f32_16x16x32_bf16 v[56:59], v[124:127], v[176:179], v[56:59]
	v_mfma_f32_16x16x32_bf16 v[44:47], v[112:115], v[186:189], v[44:47]
	v_mfma_f32_16x16x32_bf16 v[40:43], v[124:127], v[186:189], v[40:43]
	v_mfma_f32_16x16x32_bf16 v[28:31], v[112:115], v[198:201], v[28:31]
	v_mfma_f32_16x16x32_bf16 v[24:27], v[124:127], v[198:201], v[24:27]
	v_mfma_f32_16x16x32_bf16 v[12:15], v[112:115], v[206:209], v[12:15]
	v_mfma_f32_16x16x32_bf16 v[8:11], v[124:127], v[206:209], v[8:11]
	s_setprio 0
	s_setprio 1
	v_mfma_f32_16x16x32_bf16 v[52:55], v[156:159], v[172:175], v[52:55]
	v_mfma_f32_16x16x32_bf16 v[48:51], v[164:167], v[172:175], v[48:51]
	v_mfma_f32_16x16x32_bf16 v[36:39], v[156:159], v[180:183], v[36:39]
	v_mfma_f32_16x16x32_bf16 v[32:35], v[164:167], v[180:183], v[32:35]
	v_mfma_f32_16x16x32_bf16 v[20:23], v[156:159], v[194:197], v[20:23]
	v_mfma_f32_16x16x32_bf16 v[16:19], v[164:167], v[194:197], v[16:19]
	v_mfma_f32_16x16x32_bf16 v[4:7], v[156:159], v[202:205], v[4:7]
	v_mfma_f32_16x16x32_bf16 v[0:3], v[164:167], v[202:205], v[0:3]
	v_mfma_f32_16x16x32_bf16 v[52:55], v[160:163], v[176:179], v[52:55]
	v_mfma_f32_16x16x32_bf16 v[48:51], v[168:171], v[176:179], v[48:51]
	v_mfma_f32_16x16x32_bf16 v[36:39], v[160:163], v[186:189], v[36:39]
	v_mfma_f32_16x16x32_bf16 v[32:35], v[168:171], v[186:189], v[32:35]
	v_mfma_f32_16x16x32_bf16 v[20:23], v[160:163], v[198:201], v[20:23]
	v_mfma_f32_16x16x32_bf16 v[16:19], v[168:171], v[198:201], v[16:19]
	v_mfma_f32_16x16x32_bf16 v[4:7], v[160:163], v[206:209], v[4:7]
	v_mfma_f32_16x16x32_bf16 v[0:3], v[168:171], v[206:209], v[0:3]
	s_setprio 0
	s_barrier
	s_add_i32 s15, s15, 2
	s_add_u32 s56, s56, 0x100
	s_addc_u32 s57, s57, 0
	s_add_u32 s77, s77, 0x100
	s_addc_u32 s14, s14, 0
	s_cmp_gt_u32 s15, 13
	s_cbranch_scc1 .LBB0_921

; #define PG8_STAGE(bufoff, gbase, voff) do { _Pragma("unroll") for (int _i = 0; _i < 2; ++_i) \
;         __builtin_amdgcn_global_load_lds((const unsigned*)((const char*)(gbase) + (voff)[_i]), (PG8_LAS unsigned*)(lds + (bufoff) + ldsw + _i * 8192), 16, 0, 0); } while (0)
; #define PG8_WAIT_V(n) asm volatile("s_waitcnt vmcnt(" #n ")" ::: "memory")
; #define PG8_BAR __builtin_amdgcn_s_barrier()
; template <class Epi, class Sched, bool ALIGN_EPI = false, bool SP2 = false>
; __device__ __forceinline__ void gemm_phase(PG8_LAS unsigned char* lds, const Gemm g, const Sched& S, const Epi& E, const int tid_in) {
;     ...
;     if constexpr (SP2) {
;         PG8_STAGE(PG8_SB(0, 0), cB, voffB); PG8_STAGE(PG8_SB(0, 1), cB + hstep, voffB); PG8_STAGE(PG8_SA(0, 0), cA, voffA); PG8_STAGE(PG8_SA(0, 1), cA + hstepA, voffA);
;         if (wr == 1) PG8_BAR;
;         PG8_WAIT_V(2); PG8_BAR;
;         PG8_STAGE(PG8_SB(1, 0), cB + kstep, voffB); PG8_STAGE(PG8_SA(1, 0), cA + kstepA, voffA); PG8_STAGE(PG8_SB(1, 1), cB + hstep + kstep, voffB);
;         PG8_WAIT_V(6); PG8_BAR;
.LBB0_1225:
	v_and_b32_e32 v11, 48, v5
	s_waitcnt vmcnt(0)
	v_lshlrev_b32_e32 v16, 6, v5
	s_movk_i32 s7, 0x3c0
	v_lshlrev_b32_e32 v5, 2, v5
	s_lshl_b32 s6, s12, 13
	v_and_or_b32 v11, v16, s7, v11
	v_and_b32_e32 v5, 32, v5
	v_readlane_b32 s56, v255, 8
	v_bitop3_b32 v16, v11, s6, v5 bitop3:0xde
	s_lshl_b32 s6, s14, 5
	v_mov_b32_e32 v129, v185
	v_readlane_b32 s57, v255, 9
	s_and_b32 s65, s6, 0x60
	s_add_i32 m0, s35, 0x18000
	v_lshl_add_u64 v[0:1], v[0:1], 0, s[84:85]
	v_lshl_add_u64 v[12:13], s[56:57], 0, v[128:129]
	v_mov_b32_e32 v131, v185
	s_lshl_b32 s64, s12, 6
	s_lshl_b32 s6, s65, 7
	s_waitcnt vmcnt(2)
	s_barrier
	global_load_lds_dwordx4 v[0:1], off
	v_lshl_add_u64 v[0:1], v[2:3], 0, s[84:85]
	s_add_i32 m0, s35, 0x1a000
	s_add_i32 s66, s35, 0x8000
	s_add_i32 s67, s35, 0xa000
	v_lshl_add_u64 v[14:15], s[56:57], 0, v[130:131]
	global_load_lds_dwordx4 v[0:1], off
	v_lshl_add_u64 v[0:1], v[12:13], 0, s[84:85]
	s_mov_b32 m0, s66
	s_add_u32 s14, s58, 0x40080
	global_load_lds_dwordx4 v[0:1], off
	v_lshl_add_u64 v[0:1], v[14:15], 0, s[84:85]
	s_mov_b32 m0, s67
	s_addc_u32 s15, s59, 0
	global_load_lds_dwordx4 v[0:1], off
	s_add_i32 m0, s35, 0x1c000
	v_lshl_add_u64 v[0:1], s[14:15], 0, v[184:185]
	global_load_lds_dwordx4 v[0:1], off
	v_lshl_add_u64 v[0:1], s[14:15], 0, v[132:133]
	s_add_i32 m0, s35, 0x1e000
	v_bitop3_b32 v138, s6, v11, v5 bitop3:0xf6
	global_load_lds_dwordx4 v[0:1], off
	v_lshlrev_b32_e32 v0, 14, v4
	v_and_b32_e32 v0, 0xffff8000, v0
	v_lshl_add_u32 v0, v6, 11, v0
	v_and_b32_e32 v1, 1, v4
	v_lshl_or_b32 v0, v1, 6, v0
	v_lshl_add_u32 v134, v7, 1, v0
	v_lshlrev_b32_e32 v0, 14, v8
	v_and_b32_e32 v0, 0xffff8000, v0
	s_waitcnt vmcnt(6)
	v_lshl_add_u32 v0, v9, 11, v0
	v_and_b32_e32 v1, 1, v8
	s_cmpk_lt_u32 s3, 0x100
	v_lshl_or_b32 v0, v1, 6, v0
	v_readlane_b32 s6, v255, 5
	s_cselect_b64 s[40:41], -1, 0
	v_mov_b32_e32 v135, v185
	v_lshl_add_u32 v136, v10, 1, v0
	v_mov_b32_e32 v137, v185
	s_mov_b32 s70, 0
	v_add_u32_e32 v139, 0, v16
	v_readlane_b32 s71, v255, 2
	s_mov_b32 s69, s6
	s_barrier
	v_readlane_b32 s7, v255, 6
	s_mov_b32 s100, 0
	s_branch .LBB0_1228

; #define PG8_BAR __builtin_amdgcn_s_barrier()
; template <class Epi, class Sched, bool ALIGN_EPI = false, bool SP2 = false>
; __device__ __forceinline__ void gemm_phase(PG8_LAS unsigned char* lds, const Gemm g, const Sched& S, const Epi& E, const int tid_in) {
;     ...
;         cur = nxt; cA = nA; cB = nB; ++ui;
;         if constexpr (ALIGN_EPI) { if (wr == 1) PG8_BAR; }
.LBB0_1227:
	s_mov_b32 s100, 1
	s_mov_b64 s[58:59], s[50:51]
	v_readlane_b32 s50, v251, 3
	s_andn2_b64 vcc, exec, s[36:37]
	s_mov_b32 s71, s42
	s_mov_b32 s69, s44
	s_mov_b64 s[56:57], s[46:47]
	s_mov_b32 s70, s68
	v_readlane_b32 s51, v251, 4
	s_mov_b32 s55, 0x1a000000
	s_movk_i32 s79, 0x3fff
	s_cbranch_vccz .LBB0_1245

; #define PG8_STAGE(bufoff, gbase, voff) do { _Pragma("unroll") for (int _i = 0; _i < 2; ++_i) \
;         __builtin_amdgcn_global_load_lds((const unsigned*)((const char*)(gbase) + (voff)[_i]), (PG8_LAS unsigned*)(lds + (bufoff) + ldsw + _i * 8192), 16, 0, 0); } while (0)
; #define PG8_LDA(dst, b, h) do { _Pragma("unroll") for (int m = 0; m < 4; ++m) _Pragma("unroll") for (int k = 0; k < 2; ++k) dst[m][k] = *(const PG8_LAS bf16x8*)(lds + PG8_SA(b, h) + aoff + m * 2048 + k * 1024); } while (0)
; #define PG8_LDB(dst, b, h) do { _Pragma("unroll") for (int n = 0; n < 2; ++n) _Pragma("unroll") for (int k = 0; k < 2; ++k) dst[n][k] = *(const PG8_LAS bf16x8*)(lds + PG8_SB(b, h) + boff + n * 2048 + k * 1024); } while (0)
; #define PG8_MMA(ai, bj, At, Bt) do { __builtin_amdgcn_s_setprio(1); _Pragma("unroll") for (int m = 0; m < 4; ++m) _Pragma("unroll") for (int n = 0; n < 2; ++n) _Pragma("unroll") for (int k = 0; k < 2; ++k) \
;         acc[ai][bj][m][n] = __builtin_amdgcn_mfma_f32_16x16x32_bf16(Bt[n][k], At[m][k], acc[ai][bj][m][n], 0, 0, 0); __builtin_amdgcn_s_setprio(0); } while (0)
; #define PG8_WAIT_V(n) asm volatile("s_waitcnt vmcnt(" #n ")" ::: "memory")
; #define PG8_WAIT_L(n) asm volatile("s_waitcnt lgkmcnt(" #n ")" ::: "memory")
; #define PG8_BAR __builtin_amdgcn_s_barrier()
; #define PG8_SCHED __builtin_amdgcn_sched_barrier(0)
; template <class Epi, class Sched, bool ALIGN_EPI = false, bool SP2 = false>
; __device__ __forceinline__ void gemm_phase(PG8_LAS unsigned char* lds, const Gemm g, const Sched& S, const Epi& E, const int tid_in) {
;     ...
;             PG8_LDB(B0, 0, 0); PG8_LDB(B1, 0, 1); PG8_SCHED; PG8_LDA(At, 0, 0); PG8_STAGE(PG8_SA(1, 1), a1 + hstepA, voffA);
;             PG8_WAIT_V(8); PG8_WAIT_L(0); PG8_BAR; PG8_MMA(0, 0, At, B0); PG8_MMA(0, 1, At, B1); PG8_BAR; PG8_SCHED;
.LBB0_1236:
	s_add_u32 s6, s56, 0xfffc0080
	s_addc_u32 s7, s57, -1
	s_and_b64 s[58:59], s[58:59], exec
	s_cselect_b32 s61, s3, s7
	s_cselect_b32 s60, s12, s6
	s_cselect_b32 s59, s14, s53
	s_cselect_b32 s58, s15, s52
	s_add_i32 s6, 0, 0x10000
	s_add_i32 s7, 0, 0x14000
	v_add_u32_e32 v152, s6, v138
	v_add_u32_e32 v168, s7, v138
	ds_read_b128 v[140:143], v152
	ds_read_b128 v[144:147], v152 offset:1024
	ds_read_b128 v[148:151], v152 offset:2048
	ds_read_b128 v[152:155], v152 offset:3072
	ds_read_b128 v[156:159], v168
	ds_read_b128 v[160:163], v168 offset:1024
	ds_read_b128 v[164:167], v168 offset:2048
	ds_read_b128 v[168:171], v168 offset:3072
	v_lshl_add_u64 v[190:191], s[56:57], 0, v[134:135]
	s_add_i32 m0, s35, 0xc000
	ds_read_b128 v[172:175], v139
	ds_read_b128 v[176:179], v139 offset:1024
	ds_read_b128 v[180:183], v139 offset:2048
	ds_read_b128 v[186:189], v139 offset:3072
	ds_read_b128 v[194:197], v139 offset:4096
	ds_read_b128 v[198:201], v139 offset:5120
	ds_read_b128 v[202:205], v139 offset:6144
	ds_read_b128 v[206:209], v139 offset:7168
	global_load_lds_dwordx4 v[190:191], off
	v_lshl_add_u64 v[190:191], s[56:57], 0, v[136:137]
	s_add_i32 m0, s35, 0xe000
	s_nop 0
	global_load_lds_dwordx4 v[190:191], off
	s_cmp_eq_u32 s100, 0
	s_cbranch_scc1 .Llbb0_1236_strict1
	s_waitcnt vmcnt(24)
	s_branch .Llbb0_1236_done1

; #define PG8_STAGE(bufoff, gbase, voff) do { _Pragma("unroll") for (int _i = 0; _i < 2; ++_i) \
;         __builtin_amdgcn_global_load_lds((const unsigned*)((const char*)(gbase) + (voff)[_i]), (PG8_LAS unsigned*)(lds + (bufoff) + ldsw + _i * 8192), 16, 0, 0); } while (0)
; #define PG8_LDA(dst, b, h) do { _Pragma("unroll") for (int m = 0; m < 4; ++m) _Pragma("unroll") for (int k = 0; k < 2; ++k) dst[m][k] = *(const PG8_LAS bf16x8*)(lds + PG8_SA(b, h) + aoff + m * 2048 + k * 1024); } while (0)
; #define PG8_MMA(ai, bj, At, Bt) do { __builtin_amdgcn_s_setprio(1); _Pragma("unroll") for (int m = 0; m < 4; ++m) _Pragma("unroll") for (int n = 0; n < 2; ++n) _Pragma("unroll") for (int k = 0; k < 2; ++k) \
;         acc[ai][bj][m][n] = __builtin_amdgcn_mfma_f32_16x16x32_bf16(Bt[n][k], At[m][k], acc[ai][bj][m][n], 0, 0, 0); __builtin_amdgcn_s_setprio(0); } while (0)
; #define PG8_WAIT_V(n) asm volatile("s_waitcnt vmcnt(" #n ")" ::: "memory")
; #define PG8_WAIT_L(n) asm volatile("s_waitcnt lgkmcnt(" #n ")" ::: "memory")
; #define PG8_BAR __builtin_amdgcn_s_barrier()
; #define PG8_SCHED __builtin_amdgcn_sched_barrier(0)
; template <class Epi, class Sched, bool ALIGN_EPI = false, bool SP2 = false>
; __device__ __forceinline__ void gemm_phase(PG8_LAS unsigned char* lds, const Gemm g, const Sched& S, const Epi& E, const int tid_in) {
;     ...
;             PG8_WAIT_V(8); PG8_WAIT_L(0); PG8_BAR; PG8_MMA(0, 0, At, B0); PG8_MMA(0, 1, At, B1); PG8_BAR; PG8_SCHED;
;             PG8_LDA(At, 0, 1); PG8_STAGE(PG8_SB(0, 0), b2, voffB); PG8_STAGE(PG8_SB(0, 1), b2 + hstep, voffB); PG8_STAGE(PG8_SA(0, 0), a2, voffA);
.Llbb0_1236_done1:
	s_waitcnt lgkmcnt(0)
	s_barrier
	s_setprio 1
	s_waitcnt lgkmcnt(0)
	v_mfma_f32_16x16x32_bf16 v[124:127], v[140:143], v[172:175], v[124:127]
	v_mfma_f32_16x16x32_bf16 v[120:123], v[148:151], v[172:175], v[120:123]
	v_mfma_f32_16x16x32_bf16 v[108:111], v[140:143], v[180:183], v[108:111]
	v_mfma_f32_16x16x32_bf16 v[104:107], v[148:151], v[180:183], v[104:107]
	v_mfma_f32_16x16x32_bf16 v[92:95], v[140:143], v[194:197], v[92:95]
	v_mfma_f32_16x16x32_bf16 v[88:91], v[148:151], v[194:197], v[88:91]
	v_mfma_f32_16x16x32_bf16 v[76:79], v[140:143], v[202:205], v[76:79]
	v_mfma_f32_16x16x32_bf16 v[72:75], v[148:151], v[202:205], v[72:75]
	v_mfma_f32_16x16x32_bf16 v[124:127], v[144:147], v[176:179], v[124:127]
	v_mfma_f32_16x16x32_bf16 v[120:123], v[152:155], v[176:179], v[120:123]
	v_mfma_f32_16x16x32_bf16 v[108:111], v[144:147], v[186:189], v[108:111]
	v_mfma_f32_16x16x32_bf16 v[104:107], v[152:155], v[186:189], v[104:107]
	v_mfma_f32_16x16x32_bf16 v[92:95], v[144:147], v[198:201], v[92:95]
	v_mfma_f32_16x16x32_bf16 v[88:91], v[152:155], v[198:201], v[88:91]
	v_mfma_f32_16x16x32_bf16 v[76:79], v[144:147], v[206:209], v[76:79]
	v_mfma_f32_16x16x32_bf16 v[72:75], v[152:155], v[206:209], v[72:75]
	s_setprio 0
	s_setprio 1
	v_mfma_f32_16x16x32_bf16 v[116:119], v[156:159], v[172:175], v[116:119]
	v_mfma_f32_16x16x32_bf16 v[112:115], v[164:167], v[172:175], v[112:115]
	v_mfma_f32_16x16x32_bf16 v[100:103], v[156:159], v[180:183], v[100:103]
	v_mfma_f32_16x16x32_bf16 v[96:99], v[164:167], v[180:183], v[96:99]
	v_mfma_f32_16x16x32_bf16 v[84:87], v[156:159], v[194:197], v[84:87]
	v_mfma_f32_16x16x32_bf16 v[80:83], v[164:167], v[194:197], v[80:83]
	v_mfma_f32_16x16x32_bf16 v[68:71], v[156:159], v[202:205], v[68:71]
	v_mfma_f32_16x16x32_bf16 v[64:67], v[164:167], v[202:205], v[64:67]
	v_mfma_f32_16x16x32_bf16 v[116:119], v[160:163], v[176:179], v[116:119]
	v_mfma_f32_16x16x32_bf16 v[112:115], v[168:171], v[176:179], v[112:115]
	v_mfma_f32_16x16x32_bf16 v[100:103], v[160:163], v[186:189], v[100:103]
	v_mfma_f32_16x16x32_bf16 v[96:99], v[168:171], v[186:189], v[96:99]
	v_mfma_f32_16x16x32_bf16 v[84:87], v[160:163], v[198:201], v[84:87]
	v_mfma_f32_16x16x32_bf16 v[80:83], v[168:171], v[198:201], v[80:83]
	v_mfma_f32_16x16x32_bf16 v[68:71], v[160:163], v[206:209], v[68:71]
	v_mfma_f32_16x16x32_bf16 v[64:67], v[168:171], v[206:209], v[64:67]
	s_setprio 0
	s_barrier
	s_add_i32 s6, s6, s34
	v_lshl_add_u64 v[190:191], s[58:59], 0, v[184:185]
	s_mov_b32 m0, s6
	ds_read_b128 v[172:175], v139 offset:16384
	ds_read_b128 v[176:179], v139 offset:17408
	ds_read_b128 v[180:183], v139 offset:18432
	ds_read_b128 v[186:189], v139 offset:19456
	ds_read_b128 v[194:197], v139 offset:20480
	ds_read_b128 v[198:201], v139 offset:21504
	ds_read_b128 v[202:205], v139 offset:22528
	ds_read_b128 v[206:209], v139 offset:23552
	global_load_lds_dwordx4 v[190:191], off
	s_add_i32 m0, s6, 0x2000
	s_add_u32 s78, s58, 0x40000
	v_lshl_add_u64 v[192:193], s[58:59], 0, v[132:133]
	s_addc_u32 s79, s59, 0
	s_add_i32 s6, s7, s34
	global_load_lds_dwordx4 v[192:193], off
	v_lshl_add_u64 v[210:211], s[78:79], 0, v[184:185]
	s_mov_b32 m0, s6
	v_lshl_add_u64 v[212:213], s[60:61], 0, v[130:131]
	global_load_lds_dwordx4 v[210:211], off
	v_lshl_add_u64 v[210:211], s[78:79], 0, v[132:133]
	s_add_i32 m0, s6, 0x2000
	s_nop 0
	global_load_lds_dwordx4 v[210:211], off
	v_lshl_add_u64 v[210:211], s[60:61], 0, v[128:129]
	s_mov_b32 m0, s35
	s_nop 0
	global_load_lds_dwordx4 v[210:211], off
	s_mov_b32 m0, s54
	s_nop 0
	global_load_lds_dwordx4 v[212:213], off
	s_cmp_eq_u32 s100, 0
	s_cbranch_scc1 .Llbb0_1236_strict2
	s_waitcnt vmcnt(24)
	s_branch .Llbb0_1236_done2

; #define PG8_STAGE(bufoff, gbase, voff) do { _Pragma("unroll") for (int _i = 0; _i < 2; ++_i) \
;         __builtin_amdgcn_global_load_lds((const unsigned*)((const char*)(gbase) + (voff)[_i]), (PG8_LAS unsigned*)(lds + (bufoff) + ldsw + _i * 8192), 16, 0, 0); } while (0)
; #define PG8_LDA(dst, b, h) do { _Pragma("unroll") for (int m = 0; m < 4; ++m) _Pragma("unroll") for (int k = 0; k < 2; ++k) dst[m][k] = *(const PG8_LAS bf16x8*)(lds + PG8_SA(b, h) + aoff + m * 2048 + k * 1024); } while (0)
; #define PG8_LDB(dst, b, h) do { _Pragma("unroll") for (int n = 0; n < 2; ++n) _Pragma("unroll") for (int k = 0; k < 2; ++k) dst[n][k] = *(const PG8_LAS bf16x8*)(lds + PG8_SB(b, h) + boff + n * 2048 + k * 1024); } while (0)
; #define PG8_MMA(ai, bj, At, Bt) do { __builtin_amdgcn_s_setprio(1); _Pragma("unroll") for (int m = 0; m < 4; ++m) _Pragma("unroll") for (int n = 0; n < 2; ++n) _Pragma("unroll") for (int k = 0; k < 2; ++k) \
;         acc[ai][bj][m][n] = __builtin_amdgcn_mfma_f32_16x16x32_bf16(Bt[n][k], At[m][k], acc[ai][bj][m][n], 0, 0, 0); __builtin_amdgcn_s_setprio(0); } while (0)
; #define PG8_WAIT_V(n) asm volatile("s_waitcnt vmcnt(" #n ")" ::: "memory")
; #define PG8_WAIT_L(n) asm volatile("s_waitcnt lgkmcnt(" #n ")" ::: "memory")
; #define PG8_BAR __builtin_amdgcn_s_barrier()
; #define PG8_SCHED __builtin_amdgcn_sched_barrier(0)
; template <class Epi, class Sched, bool ALIGN_EPI = false, bool SP2 = false>
; __device__ __forceinline__ void gemm_phase(PG8_LAS unsigned char* lds, const Gemm g, const Sched& S, const Epi& E, const int tid_in) {
;     ...
;             PG8_LDA(At, 0, 1); PG8_STAGE(PG8_SB(0, 0), b2, voffB); PG8_STAGE(PG8_SB(0, 1), b2 + hstep, voffB); PG8_STAGE(PG8_SA(0, 0), a2, voffA);
;             PG8_WAIT_V(8); PG8_WAIT_L(0); PG8_BAR; PG8_MMA(1, 0, At, B0); PG8_MMA(1, 1, At, B1); PG8_BAR; PG8_SCHED;
;             PG8_LDB(B0, 1, 0); PG8_LDB(B1, 1, 1); PG8_SCHED; PG8_LDA(At, 1, 0); PG8_STAGE(PG8_SA(0, 1), a2 + hstepA, voffA);
;             PG8_WAIT_V(8); PG8_WAIT_L(0); PG8_BAR; PG8_MMA(0, 0, At, B0); PG8_MMA(0, 1, At, B1); PG8_BAR; PG8_SCHED;
.Llbb0_1236_done2:
	s_mov_b32 s100, 0
	s_waitcnt lgkmcnt(0)
	s_barrier
	s_setprio 1
	s_waitcnt lgkmcnt(0)
	v_mfma_f32_16x16x32_bf16 v[60:63], v[140:143], v[172:175], v[60:63]
	v_mfma_f32_16x16x32_bf16 v[56:59], v[148:151], v[172:175], v[56:59]
	v_mfma_f32_16x16x32_bf16 v[44:47], v[140:143], v[180:183], v[44:47]
	v_mfma_f32_16x16x32_bf16 v[40:43], v[148:151], v[180:183], v[40:43]
	v_mfma_f32_16x16x32_bf16 v[28:31], v[140:143], v[194:197], v[28:31]
	v_mfma_f32_16x16x32_bf16 v[24:27], v[148:151], v[194:197], v[24:27]
	v_mfma_f32_16x16x32_bf16 v[12:15], v[140:143], v[202:205], v[12:15]
	v_mfma_f32_16x16x32_bf16 v[8:11], v[148:151], v[202:205], v[8:11]
	v_mfma_f32_16x16x32_bf16 v[60:63], v[144:147], v[176:179], v[60:63]
	v_mfma_f32_16x16x32_bf16 v[56:59], v[152:155], v[176:179], v[56:59]
	v_mfma_f32_16x16x32_bf16 v[44:47], v[144:147], v[186:189], v[44:47]
	v_mfma_f32_16x16x32_bf16 v[40:43], v[152:155], v[186:189], v[40:43]
	v_mfma_f32_16x16x32_bf16 v[28:31], v[144:147], v[198:201], v[28:31]
	v_mfma_f32_16x16x32_bf16 v[24:27], v[152:155], v[198:201], v[24:27]
	v_mfma_f32_16x16x32_bf16 v[12:15], v[144:147], v[206:209], v[12:15]
	v_mfma_f32_16x16x32_bf16 v[8:11], v[152:155], v[206:209], v[8:11]
	s_setprio 0
	s_setprio 1
	v_mfma_f32_16x16x32_bf16 v[52:55], v[156:159], v[172:175], v[52:55]
	v_mfma_f32_16x16x32_bf16 v[48:51], v[164:167], v[172:175], v[48:51]
	v_mfma_f32_16x16x32_bf16 v[36:39], v[156:159], v[180:183], v[36:39]
	v_mfma_f32_16x16x32_bf16 v[32:35], v[164:167], v[180:183], v[32:35]
	v_mfma_f32_16x16x32_bf16 v[20:23], v[156:159], v[194:197], v[20:23]
	v_mfma_f32_16x16x32_bf16 v[16:19], v[164:167], v[194:197], v[16:19]
	v_mfma_f32_16x16x32_bf16 v[4:7], v[156:159], v[202:205], v[4:7]
	v_mfma_f32_16x16x32_bf16 v[0:3], v[164:167], v[202:205], v[0:3]
	v_mfma_f32_16x16x32_bf16 v[52:55], v[160:163], v[176:179], v[52:55]
	v_mfma_f32_16x16x32_bf16 v[48:51], v[168:171], v[176:179], v[48:51]
	v_mfma_f32_16x16x32_bf16 v[36:39], v[160:163], v[186:189], v[36:39]
	v_mfma_f32_16x16x32_bf16 v[32:35], v[168:171], v[186:189], v[32:35]
	v_mfma_f32_16x16x32_bf16 v[20:23], v[160:163], v[198:201], v[20:23]
	v_mfma_f32_16x16x32_bf16 v[16:19], v[168:171], v[198:201], v[16:19]
	v_mfma_f32_16x16x32_bf16 v[4:7], v[160:163], v[206:209], v[4:7]
	v_mfma_f32_16x16x32_bf16 v[0:3], v[168:171], v[206:209], v[0:3]
	s_setprio 0
	s_barrier
	s_add_i32 s6, 0, 0x18000
	s_add_i32 s7, 0, 0x1c000
	v_add_u32_e32 v152, s6, v138
	v_add_u32_e32 v168, s7, v138
	ds_read_b128 v[140:143], v152
	ds_read_b128 v[144:147], v152 offset:1024
	ds_read_b128 v[148:151], v152 offset:2048
	ds_read_b128 v[152:155], v152 offset:3072
	ds_read_b128 v[156:159], v168
	ds_read_b128 v[160:163], v168 offset:1024
	ds_read_b128 v[164:167], v168 offset:2048
	ds_read_b128 v[168:171], v168 offset:3072
	s_add_u32 s60, s60, 0x40000
	s_addc_u32 s61, s61, 0
	s_mov_b32 m0, s62
	v_lshl_add_u64 v[214:215], s[60:61], 0, v[128:129]
	ds_read_b128 v[172:175], v139 offset:32768
	ds_read_b128 v[176:179], v139 offset:33792
	ds_read_b128 v[180:183], v139 offset:34816
	ds_read_b128 v[186:189], v139 offset:35840
	ds_read_b128 v[194:197], v139 offset:36864
	ds_read_b128 v[198:201], v139 offset:37888
	ds_read_b128 v[202:205], v139 offset:38912
	ds_read_b128 v[206:209], v139 offset:39936
	global_load_lds_dwordx4 v[214:215], off
	v_lshl_add_u64 v[214:215], s[60:61], 0, v[130:131]
	s_mov_b32 m0, s63
	s_nop 0
	global_load_lds_dwordx4 v[214:215], off
	s_waitcnt vmcnt(8)
	s_waitcnt lgkmcnt(0)
	s_barrier
	s_setprio 1
	s_waitcnt lgkmcnt(0)
	v_mfma_f32_16x16x32_bf16 v[124:127], v[140:143], v[172:175], v[124:127]
	v_mfma_f32_16x16x32_bf16 v[120:123], v[148:151], v[172:175], v[120:123]
	v_mfma_f32_16x16x32_bf16 v[108:111], v[140:143], v[180:183], v[108:111]
	v_mfma_f32_16x16x32_bf16 v[104:107], v[148:151], v[180:183], v[104:107]
	v_mfma_f32_16x16x32_bf16 v[92:95], v[140:143], v[194:197], v[92:95]
	v_mfma_f32_16x16x32_bf16 v[88:91], v[148:151], v[194:197], v[88:91]
	v_mfma_f32_16x16x32_bf16 v[76:79], v[140:143], v[202:205], v[76:79]
	v_mfma_f32_16x16x32_bf16 v[72:75], v[148:151], v[202:205], v[72:75]
	v_mfma_f32_16x16x32_bf16 v[124:127], v[144:147], v[176:179], v[124:127]
	v_mfma_f32_16x16x32_bf16 v[120:123], v[152:155], v[176:179], v[120:123]
	v_mfma_f32_16x16x32_bf16 v[108:111], v[144:147], v[186:189], v[108:111]
	v_mfma_f32_16x16x32_bf16 v[104:107], v[152:155], v[186:189], v[104:107]
	v_mfma_f32_16x16x32_bf16 v[92:95], v[144:147], v[198:201], v[92:95]
	v_mfma_f32_16x16x32_bf16 v[88:91], v[152:155], v[198:201], v[88:91]
	v_mfma_f32_16x16x32_bf16 v[76:79], v[144:147], v[206:209], v[76:79]
	v_mfma_f32_16x16x32_bf16 v[72:75], v[152:155], v[206:209], v[72:75]
	s_setprio 0
	s_setprio 1
	v_mfma_f32_16x16x32_bf16 v[116:119], v[156:159], v[172:175], v[116:119]
	v_mfma_f32_16x16x32_bf16 v[112:115], v[164:167], v[172:175], v[112:115]
	v_mfma_f32_16x16x32_bf16 v[100:103], v[156:159], v[180:183], v[100:103]
	v_mfma_f32_16x16x32_bf16 v[96:99], v[164:167], v[180:183], v[96:99]
	v_mfma_f32_16x16x32_bf16 v[84:87], v[156:159], v[194:197], v[84:87]
	v_mfma_f32_16x16x32_bf16 v[80:83], v[164:167], v[194:197], v[80:83]
	v_mfma_f32_16x16x32_bf16 v[68:71], v[156:159], v[202:205], v[68:71]
	v_mfma_f32_16x16x32_bf16 v[64:67], v[164:167], v[202:205], v[64:67]
	v_mfma_f32_16x16x32_bf16 v[116:119], v[160:163], v[176:179], v[116:119]
	v_mfma_f32_16x16x32_bf16 v[112:115], v[168:171], v[176:179], v[112:115]
	v_mfma_f32_16x16x32_bf16 v[100:103], v[160:163], v[186:189], v[100:103]
	v_mfma_f32_16x16x32_bf16 v[96:99], v[168:171], v[186:189], v[96:99]
	v_mfma_f32_16x16x32_bf16 v[84:87], v[160:163], v[198:201], v[84:87]
	v_mfma_f32_16x16x32_bf16 v[80:83], v[168:171], v[198:201], v[80:83]
	v_mfma_f32_16x16x32_bf16 v[68:71], v[160:163], v[206:209], v[68:71]
	v_mfma_f32_16x16x32_bf16 v[64:67], v[168:171], v[206:209], v[64:67]
	s_setprio 0
	s_barrier
; #define PG8_STAGE(bufoff, gbase, voff) do { _Pragma("unroll") for (int _i = 0; _i < 2; ++_i) \
;         __builtin_amdgcn_global_load_lds((const unsigned*)((const char*)(gbase) + (voff)[_i]), (PG8_LAS unsigned*)(lds + (bufoff) + ldsw + _i * 8192), 16, 0, 0); } while (0)
; #define PG8_LDA(dst, b, h) do { _Pragma("unroll") for (int m = 0; m < 4; ++m) _Pragma("unroll") for (int k = 0; k < 2; ++k) dst[m][k] = *(const PG8_LAS bf16x8*)(lds + PG8_SA(b, h) + aoff + m * 2048 + k * 1024); } while (0)
; #define PG8_MMA(ai, bj, At, Bt) do { __builtin_amdgcn_s_setprio(1); _Pragma("unroll") for (int m = 0; m < 4; ++m) _Pragma("unroll") for (int n = 0; n < 2; ++n) _Pragma("unroll") for (int k = 0; k < 2; ++k) \
;         acc[ai][bj][m][n] = __builtin_amdgcn_mfma_f32_16x16x32_bf16(Bt[n][k], At[m][k], acc[ai][bj][m][n], 0, 0, 0); __builtin_amdgcn_s_setprio(0); } while (0)
; #define PG8_WAIT_V(n) asm volatile("s_waitcnt vmcnt(" #n ")" ::: "memory")
; #define PG8_WAIT_L(n) asm volatile("s_waitcnt lgkmcnt(" #n ")" ::: "memory")
; #define PG8_BAR __builtin_amdgcn_s_barrier()
; #define PG8_SCHED __builtin_amdgcn_sched_barrier(0)
; template <class Epi, class Sched, bool ALIGN_EPI = false, bool SP2 = false>
; __device__ __forceinline__ void gemm_phase(PG8_LAS unsigned char* lds, const Gemm g, const Sched& S, const Epi& E, const int tid_in) {
;     ...
;             PG8_LDA(At, 1, 1); PG8_STAGE(PG8_SB(1, 0), b3, voffB); PG8_STAGE(PG8_SB(1, 1), b3 + hstep, voffB); PG8_STAGE(PG8_SA(1, 0), a3, voffA);
;             PG8_WAIT_V(8); PG8_WAIT_L(0); PG8_BAR; PG8_MMA(1, 0, At, B0); PG8_MMA(1, 1, At, B1); PG8_BAR; PG8_SCHED;
	s_add_i32 s6, s6, s34
	v_lshl_add_u64 v[190:191], v[190:191], 0, s[84:85]
	s_mov_b32 m0, s6
	ds_read_b128 v[172:175], v139 offset:49152
	ds_read_b128 v[176:179], v139 offset:50176
	ds_read_b128 v[180:183], v139 offset:51200
	ds_read_b128 v[186:189], v139 offset:52224
	ds_read_b128 v[194:197], v139 offset:53248
	ds_read_b128 v[198:201], v139 offset:54272
	ds_read_b128 v[202:205], v139 offset:55296
	ds_read_b128 v[206:209], v139 offset:56320
	global_load_lds_dwordx4 v[190:191], off
	s_add_i32 m0, s6, 0x2000
	s_add_u32 s58, s58, 0x40080
	v_lshl_add_u64 v[190:191], v[192:193], 0, s[84:85]
	s_addc_u32 s59, s59, 0
	s_add_i32 s6, s7, s34
	global_load_lds_dwordx4 v[190:191], off
	v_lshl_add_u64 v[190:191], s[58:59], 0, v[184:185]
	s_mov_b32 m0, s6
	s_nop 0
	global_load_lds_dwordx4 v[190:191], off
	v_lshl_add_u64 v[190:191], s[58:59], 0, v[132:133]
	s_add_i32 m0, s6, 0x2000
	s_nop 0
	global_load_lds_dwordx4 v[190:191], off
	v_lshl_add_u64 v[190:191], v[210:211], 0, s[84:85]
	s_mov_b32 m0, s66
	s_nop 0
	global_load_lds_dwordx4 v[190:191], off
	v_lshl_add_u64 v[190:191], v[212:213], 0, s[84:85]
	s_mov_b32 m0, s67
	s_nop 0
	global_load_lds_dwordx4 v[190:191], off
	s_waitcnt vmcnt(8)
	s_waitcnt lgkmcnt(0)
	s_barrier
	s_setprio 1
	s_waitcnt lgkmcnt(0)
	v_mfma_f32_16x16x32_bf16 v[60:63], v[140:143], v[172:175], v[60:63]
	v_mfma_f32_16x16x32_bf16 v[56:59], v[148:151], v[172:175], v[56:59]
	v_mfma_f32_16x16x32_bf16 v[44:47], v[140:143], v[180:183], v[44:47]
	v_mfma_f32_16x16x32_bf16 v[40:43], v[148:151], v[180:183], v[40:43]
	v_mfma_f32_16x16x32_bf16 v[28:31], v[140:143], v[194:197], v[28:31]
	v_mfma_f32_16x16x32_bf16 v[24:27], v[148:151], v[194:197], v[24:27]
	v_mfma_f32_16x16x32_bf16 v[12:15], v[140:143], v[202:205], v[12:15]
	v_mfma_f32_16x16x32_bf16 v[8:11], v[148:151], v[202:205], v[8:11]
	v_mfma_f32_16x16x32_bf16 v[60:63], v[144:147], v[176:179], v[60:63]
	v_mfma_f32_16x16x32_bf16 v[56:59], v[152:155], v[176:179], v[56:59]
	v_mfma_f32_16x16x32_bf16 v[44:47], v[144:147], v[186:189], v[44:47]
	v_mfma_f32_16x16x32_bf16 v[40:43], v[152:155], v[186:189], v[40:43]
	v_mfma_f32_16x16x32_bf16 v[28:31], v[144:147], v[198:201], v[28:31]
	v_mfma_f32_16x16x32_bf16 v[24:27], v[152:155], v[198:201], v[24:27]
	v_mfma_f32_16x16x32_bf16 v[12:15], v[144:147], v[206:209], v[12:15]
	v_mfma_f32_16x16x32_bf16 v[8:11], v[152:155], v[206:209], v[8:11]
	s_setprio 0
	s_setprio 1
	v_mfma_f32_16x16x32_bf16 v[52:55], v[156:159], v[172:175], v[52:55]
	v_mfma_f32_16x16x32_bf16 v[48:51], v[164:167], v[172:175], v[48:51]
	v_mfma_f32_16x16x32_bf16 v[36:39], v[156:159], v[180:183], v[36:39]
	v_mfma_f32_16x16x32_bf16 v[32:35], v[164:167], v[180:183], v[32:35]
	v_mfma_f32_16x16x32_bf16 v[20:23], v[156:159], v[194:197], v[20:23]
	v_mfma_f32_16x16x32_bf16 v[16:19], v[164:167], v[194:197], v[16:19]
	v_mfma_f32_16x16x32_bf16 v[4:7], v[156:159], v[202:205], v[4:7]
	v_mfma_f32_16x16x32_bf16 v[0:3], v[164:167], v[202:205], v[0:3]
	v_mfma_f32_16x16x32_bf16 v[52:55], v[160:163], v[176:179], v[52:55]
	v_mfma_f32_16x16x32_bf16 v[48:51], v[168:171], v[176:179], v[48:51]
	v_mfma_f32_16x16x32_bf16 v[36:39], v[160:163], v[186:189], v[36:39]
	v_mfma_f32_16x16x32_bf16 v[32:35], v[168:171], v[186:189], v[32:35]
	v_mfma_f32_16x16x32_bf16 v[20:23], v[160:163], v[198:201], v[20:23]
	v_mfma_f32_16x16x32_bf16 v[16:19], v[168:171], v[198:201], v[16:19]
	v_mfma_f32_16x16x32_bf16 v[4:7], v[160:163], v[206:209], v[4:7]
	v_mfma_f32_16x16x32_bf16 v[0:3], v[168:171], v[206:209], v[0:3]
	s_setprio 0
	s_barrier
	s_add_i32 s77, s77, 2
	s_add_u32 s56, s56, 0x100
	s_addc_u32 s57, s57, 0
	s_add_u32 s52, s52, 0x100
	s_addc_u32 s53, s53, 0
	s_cmp_gt_u32 s77, 13
	s_cbranch_scc1 .LBB0_1240

; __global__ void __launch_bounds__(NTHREADS) mega_fwd(Params P) {
	.amdhsa_kernel _Z8mega_fwd6Params
		.amdhsa_group_segment_fixed_size 0
		.amdhsa_private_segment_fixed_size 0
		.amdhsa_kernarg_size 488
		.amdhsa_user_sgpr_count 2
		.amdhsa_user_sgpr_dispatch_ptr 0
		.amdhsa_user_sgpr_queue_ptr 0
		.amdhsa_user_sgpr_kernarg_segment_ptr 1
		.amdhsa_user_sgpr_dispatch_id 0
		.amdhsa_user_sgpr_kernarg_preload_length 0
		.amdhsa_user_sgpr_kernarg_preload_offset 0
		.amdhsa_user_sgpr_private_segment_size 0
		.amdhsa_uses_dynamic_stack 0
		.amdhsa_enable_private_segment 0
		.amdhsa_system_sgpr_workgroup_id_x 1
		.amdhsa_system_sgpr_workgroup_id_y 0
		.amdhsa_system_sgpr_workgroup_id_z 0
		.amdhsa_system_sgpr_workgroup_info 0
		.amdhsa_system_vgpr_workitem_id 2
		.amdhsa_next_free_vgpr 256
		.amdhsa_next_free_sgpr 101
		.amdhsa_accum_offset 256
		.amdhsa_reserve_vcc 1
		.amdhsa_float_round_mode_32 0
		.amdhsa_float_round_mode_16_64 0
		.amdhsa_float_denorm_mode_32 3
		.amdhsa_float_denorm_mode_16_64 3
		.amdhsa_dx10_clamp 1
		.amdhsa_ieee_mode 1
		.amdhsa_fp16_overflow 0
		.amdhsa_tg_split 0
		.amdhsa_exception_fp_ieee_invalid_op 0
		.amdhsa_exception_fp_denorm_src 0
		.amdhsa_exception_fp_ieee_div_zero 0
		.amdhsa_exception_fp_ieee_overflow 0
		.amdhsa_exception_fp_ieee_underflow 0
		.amdhsa_exception_fp_ieee_inexact 0
		.amdhsa_exception_int_div_zero 0
	.end_amdhsa_kernel

; __global__ void __launch_bounds__(NTHREADS) mega_fwd(Params P) {
.Lfunc_end0:
	.size	_Z8mega_fwd6Params, .Lfunc_end0-_Z8mega_fwd6Params
	.set _Z8mega_fwd6Params.num_vgpr, 256
	.set _Z8mega_fwd6Params.num_agpr, 0
	.set _Z8mega_fwd6Params.numbered_sgpr, 101
	.set _Z8mega_fwd6Params.num_named_barrier, 0
	.set _Z8mega_fwd6Params.private_seg_size, 0
	.set _Z8mega_fwd6Params.uses_vcc, 1
	.set _Z8mega_fwd6Params.uses_flat_scratch, 0
	.set _Z8mega_fwd6Params.has_dyn_sized_stack, 0
	.set _Z8mega_fwd6Params.has_recursion, 0
	.set _Z8mega_fwd6Params.has_indirect_call, 0

; __global__ void __launch_bounds__(NTHREADS) mega_fwd(Params P) {
amdhsa.kernels:
  - .agpr_count:     0
    .args:
      - .offset:         0
        .size:           232
        .value_kind:     by_value
      - .offset:         232
        .size:           4
        .value_kind:     hidden_block_count_x
      - .offset:         236
        .size:           4
        .value_kind:     hidden_block_count_y
      - .offset:         240
        .size:           4
        .value_kind:     hidden_block_count_z
      - .offset:         244
        .size:           2
        .value_kind:     hidden_group_size_x
      - .offset:         246
        .size:           2
        .value_kind:     hidden_group_size_y
      - .offset:         248
        .size:           2
        .value_kind:     hidden_group_size_z
      - .offset:         250
        .size:           2
        .value_kind:     hidden_remainder_x
      - .offset:         252
        .size:           2
        .value_kind:     hidden_remainder_y
      - .offset:         254
        .size:           2
        .value_kind:     hidden_remainder_z
      - .offset:         272
        .size:           8
        .value_kind:     hidden_global_offset_x
      - .offset:         280
        .size:           8
        .value_kind:     hidden_global_offset_y
      - .offset:         288
        .size:           8
        .value_kind:     hidden_global_offset_z
      - .offset:         296
        .size:           2
        .value_kind:     hidden_grid_dims
      - .offset:         320
        .size:           8
        .value_kind:     hidden_multigrid_sync_arg
      - .offset:         352
        .size:           4
        .value_kind:     hidden_dynamic_lds_size
    .group_segment_fixed_size: 0
    .kernarg_segment_align: 8
    .kernarg_segment_size: 488
    .language:       OpenCL C
    .language_version:
      - 2
      - 0
    .max_flat_workgroup_size: 512
    .name:           _Z8mega_fwd6Params
    .private_segment_fixed_size: 0
    .sgpr_count:     107
    .sgpr_spill_count: 309
    .symbol:         _Z8mega_fwd6Params.kd
    .uniform_work_group_size: 1
    .uses_dynamic_stack: false
    .vgpr_count:     256
    .vgpr_spill_count: 0
    .wavefront_size: 64
